# in-proj epilogue: straight-line paths for gate, pooling-input and prompt-v tiles (generic path kept for q/k)
# speedup vs baseline: 1.0273x; 1.0106x over previous
.LBB0_310:
	s_add_u32 s0, s18, 0xfffc0080
	s_addc_u32 s1, s19, -1
	s_add_i32 s27, 0, 0x10000
	v_add_u32_e32 v147, s27, v139
	ds_read_b128 v[152:155], v147
	ds_read_b128 v[156:159], v147 offset:1024
	ds_read_b128 v[160:163], v147 offset:2048
	ds_read_b128 v[164:167], v147 offset:3072
	s_cmp_eq_u32 s26, 12
	s_cselect_b32 s17, s3, s1
	s_cselect_b32 s16, s13, s0
	s_cselect_b32 s1, s20, s25
	s_cselect_b32 s0, s21, s24
	v_lshl_add_u64 v[190:191], s[18:19], 0, v[142:143]
	s_add_i32 m0, s95, 0xc000
	ds_read_b128 v[168:171], v181
	ds_read_b128 v[172:175], v181 offset:1024
	ds_read_b128 v[176:179], v181 offset:2048
	ds_read_b128 v[182:185], v181 offset:3072
	ds_read_b128 v[186:189], v181 offset:4096
	ds_read_b128 v[202:205], v181 offset:5120
	ds_read_b128 v[206:209], v181 offset:6144
	ds_read_b128 v[210:213], v181 offset:7168
	global_load_lds_dwordx4 v[190:191], off
	v_lshl_add_u64 v[190:191], s[18:19], 0, v[144:145]
	s_add_i32 m0, s95, 0xe000
	s_nop 0
	global_load_lds_dwordx4 v[190:191], off
	s_waitcnt lgkmcnt(8)
	s_barrier
	s_waitcnt lgkmcnt(0)
	s_setprio 1
	s_waitcnt lgkmcnt(0)
	v_mfma_f32_16x16x32_bf16 v[124:127], v[152:155], v[168:171], v[124:127]
	v_mfma_f32_16x16x32_bf16 v[120:123], v[160:163], v[168:171], v[120:123]
	v_mfma_f32_16x16x32_bf16 v[108:111], v[152:155], v[176:179], v[108:111]
	v_mfma_f32_16x16x32_bf16 v[104:107], v[160:163], v[176:179], v[104:107]
	v_mfma_f32_16x16x32_bf16 v[92:95], v[152:155], v[186:189], v[92:95]
	v_mfma_f32_16x16x32_bf16 v[88:91], v[160:163], v[186:189], v[88:91]
	v_mfma_f32_16x16x32_bf16 v[76:79], v[152:155], v[206:209], v[76:79]
	v_mfma_f32_16x16x32_bf16 v[72:75], v[160:163], v[206:209], v[72:75]
	v_mfma_f32_16x16x32_bf16 v[124:127], v[156:159], v[172:175], v[124:127]
	v_mfma_f32_16x16x32_bf16 v[120:123], v[164:167], v[172:175], v[120:123]
	v_mfma_f32_16x16x32_bf16 v[108:111], v[156:159], v[182:185], v[108:111]
	v_mfma_f32_16x16x32_bf16 v[104:107], v[164:167], v[182:185], v[104:107]
	v_mfma_f32_16x16x32_bf16 v[92:95], v[156:159], v[202:205], v[92:95]
	v_mfma_f32_16x16x32_bf16 v[88:91], v[164:167], v[202:205], v[88:91]
	v_mfma_f32_16x16x32_bf16 v[76:79], v[156:159], v[210:213], v[76:79]
	v_mfma_f32_16x16x32_bf16 v[72:75], v[164:167], v[210:213], v[72:75]
	s_setprio 0
	s_barrier
	s_add_i32 s36, 0, 0x14000
	s_add_i32 s27, s27, s94
	v_add_u32_e32 v147, s36, v139
	v_lshl_add_u64 v[190:191], s[0:1], 0, v[132:133]
	s_mov_b32 m0, s27
	ds_read_b128 v[214:217], v147
	ds_read_b128 v[218:221], v147 offset:1024
	ds_read_b128 v[238:241], v147 offset:2048
	ds_read_b128 v[242:245], v147 offset:3072
	global_load_lds_dwordx4 v[190:191], off
	v_lshl_add_u64 v[222:223], s[0:1], 0, v[128:129]
	s_add_i32 m0, s27, 0x2000
	s_nop 0
	global_load_lds_dwordx4 v[222:223], off
	s_barrier
	s_waitcnt lgkmcnt(0)
	s_setprio 1
	s_waitcnt lgkmcnt(0)
	v_mfma_f32_16x16x32_bf16 v[116:119], v[214:217], v[168:171], v[116:119]
	v_mfma_f32_16x16x32_bf16 v[112:115], v[238:241], v[168:171], v[112:115]
	v_mfma_f32_16x16x32_bf16 v[100:103], v[214:217], v[176:179], v[100:103]
	v_mfma_f32_16x16x32_bf16 v[96:99], v[238:241], v[176:179], v[96:99]
	v_mfma_f32_16x16x32_bf16 v[84:87], v[214:217], v[186:189], v[84:87]
	v_mfma_f32_16x16x32_bf16 v[80:83], v[238:241], v[186:189], v[80:83]
	v_mfma_f32_16x16x32_bf16 v[68:71], v[214:217], v[206:209], v[68:71]
	v_mfma_f32_16x16x32_bf16 v[64:67], v[238:241], v[206:209], v[64:67]
	v_mfma_f32_16x16x32_bf16 v[116:119], v[218:221], v[172:175], v[116:119]
	v_mfma_f32_16x16x32_bf16 v[112:115], v[242:245], v[172:175], v[112:115]
	v_mfma_f32_16x16x32_bf16 v[100:103], v[218:221], v[182:185], v[100:103]
	v_mfma_f32_16x16x32_bf16 v[96:99], v[242:245], v[182:185], v[96:99]
	v_mfma_f32_16x16x32_bf16 v[84:87], v[218:221], v[202:205], v[84:87]
	v_mfma_f32_16x16x32_bf16 v[80:83], v[242:245], v[202:205], v[80:83]
	v_mfma_f32_16x16x32_bf16 v[68:71], v[218:221], v[210:213], v[68:71]
	v_mfma_f32_16x16x32_bf16 v[64:67], v[242:245], v[210:213], v[64:67]
	s_setprio 0
	s_mov_b32 m0, s95
	v_lshl_add_u64 v[246:247], s[16:17], 0, v[134:135]
	s_barrier
	ds_read_b128 v[168:171], v181 offset:16384
	ds_read_b128 v[172:175], v181 offset:17408
	ds_read_b128 v[176:179], v181 offset:18432
	ds_read_b128 v[182:185], v181 offset:19456
	ds_read_b128 v[186:189], v181 offset:20480
	ds_read_b128 v[202:205], v181 offset:21504
	ds_read_b128 v[206:209], v181 offset:22528
	ds_read_b128 v[210:213], v181 offset:23552
	global_load_lds_dwordx4 v[246:247], off
	v_lshl_add_u64 v[248:249], s[16:17], 0, v[130:131]
	s_mov_b32 m0, s96
	s_nop 0
	global_load_lds_dwordx4 v[248:249], off
	s_barrier
	s_waitcnt lgkmcnt(0)
	s_setprio 1
	s_waitcnt lgkmcnt(0)
	v_mfma_f32_16x16x32_bf16 v[60:63], v[152:155], v[168:171], v[60:63]
	v_mfma_f32_16x16x32_bf16 v[56:59], v[160:163], v[168:171], v[56:59]
	v_mfma_f32_16x16x32_bf16 v[44:47], v[152:155], v[176:179], v[44:47]
	v_mfma_f32_16x16x32_bf16 v[40:43], v[160:163], v[176:179], v[40:43]
	v_mfma_f32_16x16x32_bf16 v[28:31], v[152:155], v[186:189], v[28:31]
	v_mfma_f32_16x16x32_bf16 v[24:27], v[160:163], v[186:189], v[24:27]
	v_mfma_f32_16x16x32_bf16 v[12:15], v[152:155], v[206:209], v[12:15]
	v_mfma_f32_16x16x32_bf16 v[8:11], v[160:163], v[206:209], v[8:11]
	v_mfma_f32_16x16x32_bf16 v[60:63], v[156:159], v[172:175], v[60:63]
	v_mfma_f32_16x16x32_bf16 v[56:59], v[164:167], v[172:175], v[56:59]
	v_mfma_f32_16x16x32_bf16 v[44:47], v[156:159], v[182:185], v[44:47]
	v_mfma_f32_16x16x32_bf16 v[40:43], v[164:167], v[182:185], v[40:43]
	v_mfma_f32_16x16x32_bf16 v[28:31], v[156:159], v[202:205], v[28:31]
	v_mfma_f32_16x16x32_bf16 v[24:27], v[164:167], v[202:205], v[24:27]
	v_mfma_f32_16x16x32_bf16 v[12:15], v[156:159], v[210:213], v[12:15]
	v_mfma_f32_16x16x32_bf16 v[8:11], v[164:167], v[210:213], v[8:11]
	s_setprio 0
	s_barrier
	s_add_u32 s28, s0, 0x40000
	s_addc_u32 s29, s1, 0
	s_add_i32 s27, s36, s94
	v_lshl_add_u64 v[152:153], s[28:29], 0, v[132:133]
	s_mov_b32 m0, s27
	s_nop 0
	global_load_lds_dwordx4 v[152:153], off
	v_lshl_add_u64 v[152:153], s[28:29], 0, v[128:129]
	s_add_i32 m0, s27, 0x2000
	s_nop 0
	global_load_lds_dwordx4 v[152:153], off
	s_waitcnt vmcnt(6)
	s_barrier
	s_setprio 1
	v_mfma_f32_16x16x32_bf16 v[52:55], v[214:217], v[168:171], v[52:55]
	v_mfma_f32_16x16x32_bf16 v[48:51], v[238:241], v[168:171], v[48:51]
	v_mfma_f32_16x16x32_bf16 v[36:39], v[214:217], v[176:179], v[36:39]
	v_mfma_f32_16x16x32_bf16 v[32:35], v[238:241], v[176:179], v[32:35]
	v_mfma_f32_16x16x32_bf16 v[20:23], v[214:217], v[186:189], v[20:23]
	v_mfma_f32_16x16x32_bf16 v[16:19], v[238:241], v[186:189], v[16:19]
	v_mfma_f32_16x16x32_bf16 v[4:7], v[214:217], v[206:209], v[4:7]
	v_mfma_f32_16x16x32_bf16 v[0:3], v[238:241], v[206:209], v[0:3]
	v_mfma_f32_16x16x32_bf16 v[52:55], v[218:221], v[172:175], v[52:55]
	v_mfma_f32_16x16x32_bf16 v[48:51], v[242:245], v[172:175], v[48:51]
	v_mfma_f32_16x16x32_bf16 v[36:39], v[218:221], v[182:185], v[36:39]
	v_mfma_f32_16x16x32_bf16 v[32:35], v[242:245], v[182:185], v[32:35]
	v_mfma_f32_16x16x32_bf16 v[20:23], v[218:221], v[202:205], v[20:23]
	v_mfma_f32_16x16x32_bf16 v[16:19], v[242:245], v[202:205], v[16:19]
	v_mfma_f32_16x16x32_bf16 v[4:7], v[218:221], v[210:213], v[4:7]
	v_mfma_f32_16x16x32_bf16 v[0:3], v[242:245], v[210:213], v[0:3]
	s_setprio 0
	s_add_i32 s27, 0, 0x18000
	v_add_u32_e32 v147, s27, v139
	s_barrier
	ds_read_b128 v[152:155], v147
	ds_read_b128 v[156:159], v147 offset:1024
	ds_read_b128 v[160:163], v147 offset:2048
	ds_read_b128 v[164:167], v147 offset:3072
	s_add_u32 s16, s16, 0x40000
	s_addc_u32 s17, s17, 0
	s_mov_b32 m0, s97
	v_lshl_add_u64 v[214:215], s[16:17], 0, v[134:135]
	ds_read_b128 v[168:171], v181 offset:32768
	ds_read_b128 v[172:175], v181 offset:33792
	ds_read_b128 v[176:179], v181 offset:34816
	ds_read_b128 v[182:185], v181 offset:35840
	ds_read_b128 v[186:189], v181 offset:36864
	ds_read_b128 v[202:205], v181 offset:37888
	ds_read_b128 v[206:209], v181 offset:38912
	ds_read_b128 v[210:213], v181 offset:39936
	global_load_lds_dwordx4 v[214:215], off
	v_lshl_add_u64 v[214:215], s[16:17], 0, v[130:131]
	s_mov_b32 m0, s4
	s_nop 0
	global_load_lds_dwordx4 v[214:215], off
	s_waitcnt lgkmcnt(8)
	s_barrier
	s_waitcnt lgkmcnt(0)
	s_setprio 1
	s_waitcnt lgkmcnt(0)
	v_mfma_f32_16x16x32_bf16 v[124:127], v[152:155], v[168:171], v[124:127]
	v_mfma_f32_16x16x32_bf16 v[120:123], v[160:163], v[168:171], v[120:123]
	v_mfma_f32_16x16x32_bf16 v[108:111], v[152:155], v[176:179], v[108:111]
	v_mfma_f32_16x16x32_bf16 v[104:107], v[160:163], v[176:179], v[104:107]
	v_mfma_f32_16x16x32_bf16 v[92:95], v[152:155], v[186:189], v[92:95]
	v_mfma_f32_16x16x32_bf16 v[88:91], v[160:163], v[186:189], v[88:91]
	v_mfma_f32_16x16x32_bf16 v[76:79], v[152:155], v[206:209], v[76:79]
	v_mfma_f32_16x16x32_bf16 v[72:75], v[160:163], v[206:209], v[72:75]
	v_mfma_f32_16x16x32_bf16 v[124:127], v[156:159], v[172:175], v[124:127]
	v_mfma_f32_16x16x32_bf16 v[120:123], v[164:167], v[172:175], v[120:123]
	v_mfma_f32_16x16x32_bf16 v[108:111], v[156:159], v[182:185], v[108:111]
	v_mfma_f32_16x16x32_bf16 v[104:107], v[164:167], v[182:185], v[104:107]
	v_mfma_f32_16x16x32_bf16 v[92:95], v[156:159], v[202:205], v[92:95]
	v_mfma_f32_16x16x32_bf16 v[88:91], v[164:167], v[202:205], v[88:91]
	v_mfma_f32_16x16x32_bf16 v[76:79], v[156:159], v[210:213], v[76:79]
	v_mfma_f32_16x16x32_bf16 v[72:75], v[164:167], v[210:213], v[72:75]
	s_setprio 0
	s_barrier
	s_add_i32 s16, 0, 0x1c000
	s_add_i32 s17, s27, s94
	v_add_u32_e32 v147, s16, v139
	v_lshl_add_u64 v[190:191], v[190:191], 0, s[30:31]
	s_mov_b32 m0, s17
	ds_read_b128 v[214:217], v147
	ds_read_b128 v[218:221], v147 offset:1024
	ds_read_b128 v[238:241], v147 offset:2048
	ds_read_b128 v[242:245], v147 offset:3072
	global_load_lds_dwordx4 v[190:191], off
	v_lshl_add_u64 v[190:191], v[222:223], 0, s[30:31]
	s_add_i32 m0, s17, 0x2000
	s_nop 0
	global_load_lds_dwordx4 v[190:191], off
	s_barrier
	s_waitcnt lgkmcnt(0)
	s_setprio 1
	s_waitcnt lgkmcnt(0)
	v_mfma_f32_16x16x32_bf16 v[116:119], v[214:217], v[168:171], v[116:119]
	v_mfma_f32_16x16x32_bf16 v[112:115], v[238:241], v[168:171], v[112:115]
	v_mfma_f32_16x16x32_bf16 v[100:103], v[214:217], v[176:179], v[100:103]
	v_mfma_f32_16x16x32_bf16 v[96:99], v[238:241], v[176:179], v[96:99]
	v_mfma_f32_16x16x32_bf16 v[84:87], v[214:217], v[186:189], v[84:87]
	v_mfma_f32_16x16x32_bf16 v[80:83], v[238:241], v[186:189], v[80:83]
	v_mfma_f32_16x16x32_bf16 v[68:71], v[214:217], v[206:209], v[68:71]
	v_mfma_f32_16x16x32_bf16 v[64:67], v[238:241], v[206:209], v[64:67]
	v_mfma_f32_16x16x32_bf16 v[116:119], v[218:221], v[172:175], v[116:119]
	v_mfma_f32_16x16x32_bf16 v[112:115], v[242:245], v[172:175], v[112:115]
	v_mfma_f32_16x16x32_bf16 v[100:103], v[218:221], v[182:185], v[100:103]
	v_mfma_f32_16x16x32_bf16 v[96:99], v[242:245], v[182:185], v[96:99]
	v_mfma_f32_16x16x32_bf16 v[84:87], v[218:221], v[202:205], v[84:87]
	v_mfma_f32_16x16x32_bf16 v[80:83], v[242:245], v[202:205], v[80:83]
	v_mfma_f32_16x16x32_bf16 v[68:71], v[218:221], v[210:213], v[68:71]
	v_mfma_f32_16x16x32_bf16 v[64:67], v[242:245], v[210:213], v[64:67]
	s_setprio 0
	s_mov_b32 m0, s6
	v_lshl_add_u64 v[190:191], v[246:247], 0, s[30:31]
	s_barrier
	ds_read_b128 v[168:171], v181 offset:49152
	ds_read_b128 v[172:175], v181 offset:50176
	ds_read_b128 v[176:179], v181 offset:51200
	ds_read_b128 v[182:185], v181 offset:52224
	ds_read_b128 v[186:189], v181 offset:53248
	ds_read_b128 v[202:205], v181 offset:54272
	ds_read_b128 v[206:209], v181 offset:55296
	ds_read_b128 v[210:213], v181 offset:56320
	global_load_lds_dwordx4 v[190:191], off
	v_lshl_add_u64 v[190:191], v[248:249], 0, s[30:31]
	s_mov_b32 m0, s7
	s_nop 0
	global_load_lds_dwordx4 v[190:191], off
	s_barrier
	s_waitcnt lgkmcnt(0)
	s_setprio 1
	s_waitcnt lgkmcnt(0)
	v_mfma_f32_16x16x32_bf16 v[60:63], v[152:155], v[168:171], v[60:63]
	v_mfma_f32_16x16x32_bf16 v[56:59], v[160:163], v[168:171], v[56:59]
	v_mfma_f32_16x16x32_bf16 v[44:47], v[152:155], v[176:179], v[44:47]
	v_mfma_f32_16x16x32_bf16 v[40:43], v[160:163], v[176:179], v[40:43]
	v_mfma_f32_16x16x32_bf16 v[28:31], v[152:155], v[186:189], v[28:31]
	v_mfma_f32_16x16x32_bf16 v[24:27], v[160:163], v[186:189], v[24:27]
	v_mfma_f32_16x16x32_bf16 v[12:15], v[152:155], v[206:209], v[12:15]
	v_mfma_f32_16x16x32_bf16 v[8:11], v[160:163], v[206:209], v[8:11]
	v_mfma_f32_16x16x32_bf16 v[60:63], v[156:159], v[172:175], v[60:63]
	v_mfma_f32_16x16x32_bf16 v[56:59], v[164:167], v[172:175], v[56:59]
	v_mfma_f32_16x16x32_bf16 v[44:47], v[156:159], v[182:185], v[44:47]
	v_mfma_f32_16x16x32_bf16 v[40:43], v[164:167], v[182:185], v[40:43]
	v_mfma_f32_16x16x32_bf16 v[28:31], v[156:159], v[202:205], v[28:31]
	v_mfma_f32_16x16x32_bf16 v[24:27], v[164:167], v[202:205], v[24:27]
	v_mfma_f32_16x16x32_bf16 v[12:15], v[156:159], v[210:213], v[12:15]
	v_mfma_f32_16x16x32_bf16 v[8:11], v[164:167], v[210:213], v[8:11]
	s_setprio 0
	s_barrier
	s_add_u32 s0, s0, 0x40080
	s_addc_u32 s1, s1, 0
	s_add_i32 s16, s16, s94
	v_lshl_add_u64 v[152:153], s[0:1], 0, v[132:133]
	s_mov_b32 m0, s16
	s_nop 0
	global_load_lds_dwordx4 v[152:153], off
	v_lshl_add_u64 v[152:153], s[0:1], 0, v[128:129]
	s_add_i32 m0, s16, 0x2000
	s_nop 0
	global_load_lds_dwordx4 v[152:153], off
	s_waitcnt vmcnt(6)
	s_barrier
	s_setprio 1
	v_mfma_f32_16x16x32_bf16 v[52:55], v[214:217], v[168:171], v[52:55]
	v_mfma_f32_16x16x32_bf16 v[48:51], v[238:241], v[168:171], v[48:51]
	v_mfma_f32_16x16x32_bf16 v[36:39], v[214:217], v[176:179], v[36:39]
	v_mfma_f32_16x16x32_bf16 v[32:35], v[238:241], v[176:179], v[32:35]
	v_mfma_f32_16x16x32_bf16 v[20:23], v[214:217], v[186:189], v[20:23]
	v_mfma_f32_16x16x32_bf16 v[16:19], v[238:241], v[186:189], v[16:19]
	v_mfma_f32_16x16x32_bf16 v[4:7], v[214:217], v[206:209], v[4:7]
	v_mfma_f32_16x16x32_bf16 v[0:3], v[238:241], v[206:209], v[0:3]
	v_mfma_f32_16x16x32_bf16 v[52:55], v[218:221], v[172:175], v[52:55]
	v_mfma_f32_16x16x32_bf16 v[48:51], v[242:245], v[172:175], v[48:51]
	v_mfma_f32_16x16x32_bf16 v[36:39], v[218:221], v[182:185], v[36:39]
	v_mfma_f32_16x16x32_bf16 v[32:35], v[242:245], v[182:185], v[32:35]
	v_mfma_f32_16x16x32_bf16 v[20:23], v[218:221], v[202:205], v[20:23]
	v_mfma_f32_16x16x32_bf16 v[16:19], v[242:245], v[202:205], v[16:19]
	v_mfma_f32_16x16x32_bf16 v[4:7], v[218:221], v[210:213], v[4:7]
	v_mfma_f32_16x16x32_bf16 v[0:3], v[242:245], v[210:213], v[0:3]
	s_setprio 0
	s_add_i32 s26, s26, 2
	s_add_u32 s18, s18, 0x100
	s_addc_u32 s19, s19, 0
	s_add_u32 s24, s24, 0x100
	s_addc_u32 s25, s25, 0
	s_cmp_gt_u32 s26, 13
	s_barrier
	s_cbranch_scc0 .LBB0_310
	s_cmp_gt_u32 s33, 7
	s_cbranch_scc1 .Lepi_g
	s_cmp_lt_u32 s33, 2
	s_cbranch_scc1 .Lepi_u
	s_and_b32 s16, s33, -2
	s_cmp_eq_u32 s16, 6
	s_cbranch_scc1 .Lepi_v
	s_branch .Lepi_generic
.Lepi_g:
	s_lshl_b32 s16, s2, 19
	s_add_i32 s17, s33, -8
	s_lshl_b32 s17, s17, 13
	s_add_i32 s16, s16, s17
	s_add_u32 s16, s66, s16
	s_addc_u32 s17, s67, 0
	s_add_u32 s16, s16, 0x1c801000
	s_addc_u32 s17, s17, 0
	v_and_b32_e32 v152, 63, v224
	v_lshlrev_b32_e32 v152, 3, v152
	v_bfe_u32 v153, v224, 6, 2
	v_lshl_or_b32 v152, v153, 9, v152
	v_lshrrev_b32_e32 v153, 8, v224
	v_lshl_or_b32 v152, v153, 17, v152
	v_mov_b32_e32 v153, v152
	v_cvt_pk_bf16_f32 v154, v124, v125
	v_cvt_pk_bf16_f32 v155, v126, v127
	v_cvt_pk_bf16_f32 v156, v120, v121
	v_cvt_pk_bf16_f32 v157, v122, v123
	global_store_dwordx2 v153, v[154:155], s[16:17]
	global_store_dwordx2 v153, v[156:157], s[16:17] offset:2048
	v_add_u32_e32 v158, 0x1000, v152
	v_cvt_pk_bf16_f32 v160, v116, v117
	v_cvt_pk_bf16_f32 v161, v118, v119
	v_cvt_pk_bf16_f32 v162, v112, v113
	v_cvt_pk_bf16_f32 v163, v114, v115
	global_store_dwordx2 v158, v[160:161], s[16:17]
	global_store_dwordx2 v158, v[162:163], s[16:17] offset:2048
	v_add_u32_e32 v153, 0x8000, v152
	v_cvt_pk_bf16_f32 v154, v108, v109
	v_cvt_pk_bf16_f32 v155, v110, v111
	v_cvt_pk_bf16_f32 v156, v104, v105
	v_cvt_pk_bf16_f32 v157, v106, v107
	global_store_dwordx2 v153, v[154:155], s[16:17]
	global_store_dwordx2 v153, v[156:157], s[16:17] offset:2048
	v_add_u32_e32 v158, 0x9000, v152
	v_cvt_pk_bf16_f32 v160, v100, v101
	v_cvt_pk_bf16_f32 v161, v102, v103
	v_cvt_pk_bf16_f32 v162, v96, v97
	v_cvt_pk_bf16_f32 v163, v98, v99
	global_store_dwordx2 v158, v[160:161], s[16:17]
	global_store_dwordx2 v158, v[162:163], s[16:17] offset:2048
	v_add_u32_e32 v153, 0x10000, v152
	v_cvt_pk_bf16_f32 v154, v92, v93
	v_cvt_pk_bf16_f32 v155, v94, v95
	v_cvt_pk_bf16_f32 v156, v88, v89
	v_cvt_pk_bf16_f32 v157, v90, v91
	global_store_dwordx2 v153, v[154:155], s[16:17]
	global_store_dwordx2 v153, v[156:157], s[16:17] offset:2048
	v_add_u32_e32 v158, 0x11000, v152
	v_cvt_pk_bf16_f32 v160, v84, v85
	v_cvt_pk_bf16_f32 v161, v86, v87
	v_cvt_pk_bf16_f32 v162, v80, v81
	v_cvt_pk_bf16_f32 v163, v82, v83
	global_store_dwordx2 v158, v[160:161], s[16:17]
	global_store_dwordx2 v158, v[162:163], s[16:17] offset:2048
	v_add_u32_e32 v153, 0x18000, v152
	v_cvt_pk_bf16_f32 v154, v76, v77
	v_cvt_pk_bf16_f32 v155, v78, v79
	v_cvt_pk_bf16_f32 v156, v72, v73
	v_cvt_pk_bf16_f32 v157, v74, v75
	global_store_dwordx2 v153, v[154:155], s[16:17]
	global_store_dwordx2 v153, v[156:157], s[16:17] offset:2048
	v_add_u32_e32 v158, 0x19000, v152
	v_cvt_pk_bf16_f32 v160, v68, v69
	v_cvt_pk_bf16_f32 v161, v70, v71
	v_cvt_pk_bf16_f32 v162, v64, v65
	v_cvt_pk_bf16_f32 v163, v66, v67
	global_store_dwordx2 v158, v[160:161], s[16:17]
	global_store_dwordx2 v158, v[162:163], s[16:17] offset:2048
	v_add_u32_e32 v153, 0x40000, v152
	v_cvt_pk_bf16_f32 v154, v60, v61
	v_cvt_pk_bf16_f32 v155, v62, v63
	v_cvt_pk_bf16_f32 v156, v56, v57
	v_cvt_pk_bf16_f32 v157, v58, v59
	global_store_dwordx2 v153, v[154:155], s[16:17]
	global_store_dwordx2 v153, v[156:157], s[16:17] offset:2048
	v_add_u32_e32 v158, 0x41000, v152
	v_cvt_pk_bf16_f32 v160, v52, v53
	v_cvt_pk_bf16_f32 v161, v54, v55
	v_cvt_pk_bf16_f32 v162, v48, v49
	v_cvt_pk_bf16_f32 v163, v50, v51
	global_store_dwordx2 v158, v[160:161], s[16:17]
	global_store_dwordx2 v158, v[162:163], s[16:17] offset:2048
	v_add_u32_e32 v153, 0x48000, v152
	v_cvt_pk_bf16_f32 v154, v44, v45
	v_cvt_pk_bf16_f32 v155, v46, v47
	v_cvt_pk_bf16_f32 v156, v40, v41
	v_cvt_pk_bf16_f32 v157, v42, v43
	global_store_dwordx2 v153, v[154:155], s[16:17]
	global_store_dwordx2 v153, v[156:157], s[16:17] offset:2048
	v_add_u32_e32 v158, 0x49000, v152
	v_cvt_pk_bf16_f32 v160, v36, v37
	v_cvt_pk_bf16_f32 v161, v38, v39
	v_cvt_pk_bf16_f32 v162, v32, v33
	v_cvt_pk_bf16_f32 v163, v34, v35
	global_store_dwordx2 v158, v[160:161], s[16:17]
	global_store_dwordx2 v158, v[162:163], s[16:17] offset:2048
	v_add_u32_e32 v153, 0x50000, v152
	v_cvt_pk_bf16_f32 v154, v28, v29
	v_cvt_pk_bf16_f32 v155, v30, v31
	v_cvt_pk_bf16_f32 v156, v24, v25
	v_cvt_pk_bf16_f32 v157, v26, v27
	global_store_dwordx2 v153, v[154:155], s[16:17]
	global_store_dwordx2 v153, v[156:157], s[16:17] offset:2048
	v_add_u32_e32 v158, 0x51000, v152
	v_cvt_pk_bf16_f32 v160, v20, v21
	v_cvt_pk_bf16_f32 v161, v22, v23
	v_cvt_pk_bf16_f32 v162, v16, v17
	v_cvt_pk_bf16_f32 v163, v18, v19
	global_store_dwordx2 v158, v[160:161], s[16:17]
	global_store_dwordx2 v158, v[162:163], s[16:17] offset:2048
	v_add_u32_e32 v153, 0x58000, v152
	v_cvt_pk_bf16_f32 v154, v12, v13
	v_cvt_pk_bf16_f32 v155, v14, v15
	v_cvt_pk_bf16_f32 v156, v8, v9
	v_cvt_pk_bf16_f32 v157, v10, v11
	global_store_dwordx2 v153, v[154:155], s[16:17]
	global_store_dwordx2 v153, v[156:157], s[16:17] offset:2048
	v_add_u32_e32 v158, 0x59000, v152
	v_cvt_pk_bf16_f32 v160, v4, v5
	v_cvt_pk_bf16_f32 v161, v6, v7
	v_cvt_pk_bf16_f32 v162, v0, v1
	v_cvt_pk_bf16_f32 v163, v2, v3
	global_store_dwordx2 v158, v[160:161], s[16:17]
	global_store_dwordx2 v158, v[162:163], s[16:17] offset:2048
	s_mov_b64 s[2:3], exec
	s_branch .LBB0_306
.Lepi_u:
	s_mul_i32 s16, s2, 0x180000
	s_lshl_b32 s17, s33, 9
	s_add_i32 s16, s16, s17
	s_add_u32 s16, s66, s16
	s_addc_u32 s17, s67, 0
	s_add_u32 s16, s16, 0x6801000
	s_addc_u32 s17, s17, 0
	v_and_b32_e32 v152, 15, v224
	v_lshrrev_b32_e32 v153, 8, v224
	v_lshl_or_b32 v153, v153, 6, v152
	v_mul_u32_u24_e32 v153, 0x1800, v153
	v_bfe_u32 v164, v224, 4, 4
	v_lshl_add_u32 v152, v164, 3, v153
	v_mov_b32_e32 v153, v152
	v_cvt_pk_bf16_f32 v154, v124, v125
	v_cvt_pk_bf16_f32 v155, v126, v127
	v_cvt_pk_bf16_f32 v156, v120, v121
	v_cvt_pk_bf16_f32 v157, v122, v123
	global_store_dwordx2 v153, v[154:155], s[16:17]
	global_store_dwordx2 v153, v[156:157], s[16:17] offset:128
	v_add_u32_e32 v158, 0x100, v152
	v_cvt_pk_bf16_f32 v160, v116, v117
	v_cvt_pk_bf16_f32 v161, v118, v119
	v_cvt_pk_bf16_f32 v162, v112, v113
	v_cvt_pk_bf16_f32 v163, v114, v115
	global_store_dwordx2 v158, v[160:161], s[16:17]
	global_store_dwordx2 v158, v[162:163], s[16:17] offset:128
	v_add_u32_e32 v153, 0x18000, v152
	v_cvt_pk_bf16_f32 v154, v108, v109
	v_cvt_pk_bf16_f32 v155, v110, v111
	v_cvt_pk_bf16_f32 v156, v104, v105
	v_cvt_pk_bf16_f32 v157, v106, v107
	global_store_dwordx2 v153, v[154:155], s[16:17]
	global_store_dwordx2 v153, v[156:157], s[16:17] offset:128
	v_add_u32_e32 v158, 0x18100, v152
	v_cvt_pk_bf16_f32 v160, v100, v101
	v_cvt_pk_bf16_f32 v161, v102, v103
	v_cvt_pk_bf16_f32 v162, v96, v97
	v_cvt_pk_bf16_f32 v163, v98, v99
	global_store_dwordx2 v158, v[160:161], s[16:17]
	global_store_dwordx2 v158, v[162:163], s[16:17] offset:128
	v_add_u32_e32 v153, 0x30000, v152
	v_cvt_pk_bf16_f32 v154, v92, v93
	v_cvt_pk_bf16_f32 v155, v94, v95
	v_cvt_pk_bf16_f32 v156, v88, v89
	v_cvt_pk_bf16_f32 v157, v90, v91
	global_store_dwordx2 v153, v[154:155], s[16:17]
	global_store_dwordx2 v153, v[156:157], s[16:17] offset:128
	v_add_u32_e32 v158, 0x30100, v152
	v_cvt_pk_bf16_f32 v160, v84, v85
	v_cvt_pk_bf16_f32 v161, v86, v87
	v_cvt_pk_bf16_f32 v162, v80, v81
	v_cvt_pk_bf16_f32 v163, v82, v83
	global_store_dwordx2 v158, v[160:161], s[16:17]
	global_store_dwordx2 v158, v[162:163], s[16:17] offset:128
	v_add_u32_e32 v153, 0x48000, v152
	v_cvt_pk_bf16_f32 v154, v76, v77
	v_cvt_pk_bf16_f32 v155, v78, v79
	v_cvt_pk_bf16_f32 v156, v72, v73
	v_cvt_pk_bf16_f32 v157, v74, v75
	global_store_dwordx2 v153, v[154:155], s[16:17]
	global_store_dwordx2 v153, v[156:157], s[16:17] offset:128
	v_add_u32_e32 v158, 0x48100, v152
	v_cvt_pk_bf16_f32 v160, v68, v69
	v_cvt_pk_bf16_f32 v161, v70, v71
	v_cvt_pk_bf16_f32 v162, v64, v65
	v_cvt_pk_bf16_f32 v163, v66, v67
	global_store_dwordx2 v158, v[160:161], s[16:17]
	global_store_dwordx2 v158, v[162:163], s[16:17] offset:128
	v_add_u32_e32 v153, 0xc0000, v152
	v_cvt_pk_bf16_f32 v154, v60, v61
	v_cvt_pk_bf16_f32 v155, v62, v63
	v_cvt_pk_bf16_f32 v156, v56, v57
	v_cvt_pk_bf16_f32 v157, v58, v59
	global_store_dwordx2 v153, v[154:155], s[16:17]
	global_store_dwordx2 v153, v[156:157], s[16:17] offset:128
	v_add_u32_e32 v158, 0xc0100, v152
	v_cvt_pk_bf16_f32 v160, v52, v53
	v_cvt_pk_bf16_f32 v161, v54, v55
	v_cvt_pk_bf16_f32 v162, v48, v49
	v_cvt_pk_bf16_f32 v163, v50, v51
	global_store_dwordx2 v158, v[160:161], s[16:17]
	global_store_dwordx2 v158, v[162:163], s[16:17] offset:128
	v_add_u32_e32 v153, 0xd8000, v152
	v_cvt_pk_bf16_f32 v154, v44, v45
	v_cvt_pk_bf16_f32 v155, v46, v47
	v_cvt_pk_bf16_f32 v156, v40, v41
	v_cvt_pk_bf16_f32 v157, v42, v43
	global_store_dwordx2 v153, v[154:155], s[16:17]
	global_store_dwordx2 v153, v[156:157], s[16:17] offset:128
	v_add_u32_e32 v158, 0xd8100, v152
	v_cvt_pk_bf16_f32 v160, v36, v37
	v_cvt_pk_bf16_f32 v161, v38, v39
	v_cvt_pk_bf16_f32 v162, v32, v33
	v_cvt_pk_bf16_f32 v163, v34, v35
	global_store_dwordx2 v158, v[160:161], s[16:17]
	global_store_dwordx2 v158, v[162:163], s[16:17] offset:128
	v_add_u32_e32 v153, 0xf0000, v152
	v_cvt_pk_bf16_f32 v154, v28, v29
	v_cvt_pk_bf16_f32 v155, v30, v31
	v_cvt_pk_bf16_f32 v156, v24, v25
	v_cvt_pk_bf16_f32 v157, v26, v27
	global_store_dwordx2 v153, v[154:155], s[16:17]
	global_store_dwordx2 v153, v[156:157], s[16:17] offset:128
	v_add_u32_e32 v158, 0xf0100, v152
	v_cvt_pk_bf16_f32 v160, v20, v21
	v_cvt_pk_bf16_f32 v161, v22, v23
	v_cvt_pk_bf16_f32 v162, v16, v17
	v_cvt_pk_bf16_f32 v163, v18, v19
	global_store_dwordx2 v158, v[160:161], s[16:17]
	global_store_dwordx2 v158, v[162:163], s[16:17] offset:128
	v_add_u32_e32 v153, 0x108000, v152
	v_cvt_pk_bf16_f32 v154, v12, v13
	v_cvt_pk_bf16_f32 v155, v14, v15
	v_cvt_pk_bf16_f32 v156, v8, v9
	v_cvt_pk_bf16_f32 v157, v10, v11
	global_store_dwordx2 v153, v[154:155], s[16:17]
	global_store_dwordx2 v153, v[156:157], s[16:17] offset:128
	v_add_u32_e32 v158, 0x108100, v152
	v_cvt_pk_bf16_f32 v160, v4, v5
	v_cvt_pk_bf16_f32 v161, v6, v7
	v_cvt_pk_bf16_f32 v162, v0, v1
	v_cvt_pk_bf16_f32 v163, v2, v3
	global_store_dwordx2 v158, v[160:161], s[16:17]
	global_store_dwordx2 v158, v[162:163], s[16:17] offset:128
	s_and_b32 s18, s2, 7
	s_cmp_lg_u32 s18, 7
	s_cbranch_scc1 .Lepi_u_done
	s_lshr_b32 s18, s2, 3
	s_mul_i32 s18, s18, 0x7800
	s_lshl_b32 s19, s33, 10
	s_add_i32 s18, s18, s19
	s_add_u32 s18, s10, s18
	s_addc_u32 s19, s11, 0
	s_sub_u32 s18, s18, 0x800
	s_subb_u32 s19, s19, 0
	v_and_b32_e32 v153, 15, v224
	v_lshlrev_b32_e32 v154, 11, v153
	v_lshl_add_u32 v154, v164, 4, v154
	v_cmp_lt_u32_e32 vcc, 0xff, v224
	v_cmp_ne_u32_e64 s[20:21], 0, v153
	s_and_b64 s[20:21], vcc, s[20:21]
	s_and_saveexec_b64 s[24:25], s[20:21]
	s_cbranch_execz .Lepi_u_px
	global_store_dwordx4 v154, v[12:15], s[18:19]
	global_store_dwordx4 v154, v[8:11], s[18:19] offset:256
	global_store_dwordx4 v154, v[4:7], s[18:19] offset:512
	global_store_dwordx4 v154, v[0:3], s[18:19] offset:768

.Lepi_u_done:
	s_mov_b64 s[2:3], exec
	s_branch .LBB0_306
.Lepi_v:
	s_lshr_b32 s16, s2, 3
	s_lshl_b32 s16, s16, 2
	s_and_b32 s17, s33, 1
	s_lshl_b32 s17, s17, 1
	s_add_i32 s16, s16, s17
	s_lshl_b32 s16, s16, 6
	s_and_b32 s17, s2, 7
	s_lshl_b32 s17, s17, 3
	s_add_i32 s16, s16, s17
	s_lshl_b32 s16, s16, 13
	s_add_u32 s16, s66, s16
	s_addc_u32 s17, s67, 0
	s_add_u32 s16, s16, 0xde01000
	s_addc_u32 s17, s17, 0
	v_lshrrev_b32_e32 v152, 8, v224
	v_lshlrev_b32_e32 v152, 14, v152
	v_bfe_u32 v153, v224, 4, 4
	v_lshl_or_b32 v152, v153, 8, v152
	v_bfe_u32 v153, v224, 2, 2
	v_lshl_or_b32 v152, v153, 4, v152
	v_and_b32_e32 v153, 3, v224
	v_lshl_or_b32 v152, v153, 1, v152
	v_mov_b32_e32 v153, v152
	v_add_u32_e32 v154, 0x1000, v152
	v_bfe_u32 v155, v124, 16, 1
	v_add3_u32 v155, v124, v155, s76
	global_store_short_d16_hi v153, v155, s[16:17]
	v_bfe_u32 v156, v120, 16, 1
	v_add3_u32 v156, v120, v156, s76
	global_store_short_d16_hi v154, v156, s[16:17]
	v_bfe_u32 v157, v125, 16, 1
	v_add3_u32 v157, v125, v157, s76
	global_store_short_d16_hi v153, v157, s[16:17] offset:64
	v_bfe_u32 v158, v121, 16, 1
	v_add3_u32 v158, v121, v158, s76
	global_store_short_d16_hi v154, v158, s[16:17] offset:64
	v_bfe_u32 v155, v126, 16, 1
	v_add3_u32 v155, v126, v155, s76
	global_store_short_d16_hi v153, v155, s[16:17] offset:128
	v_bfe_u32 v156, v122, 16, 1
	v_add3_u32 v156, v122, v156, s76
	global_store_short_d16_hi v154, v156, s[16:17] offset:128
	v_bfe_u32 v157, v127, 16, 1
	v_add3_u32 v157, v127, v157, s76
	global_store_short_d16_hi v153, v157, s[16:17] offset:192
	v_bfe_u32 v158, v123, 16, 1
	v_add3_u32 v158, v123, v158, s76
	global_store_short_d16_hi v154, v158, s[16:17] offset:192
	v_add_u32_e32 v158, 0x80000, v152
	v_add_u32_e32 v159, 0x81000, v152
	v_bfe_u32 v160, v116, 16, 1
	v_add3_u32 v160, v116, v160, s76
	global_store_short_d16_hi v158, v160, s[16:17]
	v_bfe_u32 v161, v112, 16, 1
	v_add3_u32 v161, v112, v161, s76
	global_store_short_d16_hi v159, v161, s[16:17]
	v_bfe_u32 v162, v117, 16, 1
	v_add3_u32 v162, v117, v162, s76
	global_store_short_d16_hi v158, v162, s[16:17] offset:64
	v_bfe_u32 v163, v113, 16, 1
	v_add3_u32 v163, v113, v163, s76
	global_store_short_d16_hi v159, v163, s[16:17] offset:64
	v_bfe_u32 v160, v118, 16, 1
	v_add3_u32 v160, v118, v160, s76
	global_store_short_d16_hi v158, v160, s[16:17] offset:128
	v_bfe_u32 v161, v114, 16, 1
	v_add3_u32 v161, v114, v161, s76
	global_store_short_d16_hi v159, v161, s[16:17] offset:128
	v_bfe_u32 v162, v119, 16, 1
	v_add3_u32 v162, v119, v162, s76
	global_store_short_d16_hi v158, v162, s[16:17] offset:192
	v_bfe_u32 v163, v115, 16, 1
	v_add3_u32 v163, v115, v163, s76
	global_store_short_d16_hi v159, v163, s[16:17] offset:192
	v_add_u32_e32 v153, 0x8, v152
	v_add_u32_e32 v154, 0x1008, v152
	v_bfe_u32 v155, v108, 16, 1
	v_add3_u32 v155, v108, v155, s76
	global_store_short_d16_hi v153, v155, s[16:17]
	v_bfe_u32 v156, v104, 16, 1
	v_add3_u32 v156, v104, v156, s76
	global_store_short_d16_hi v154, v156, s[16:17]
	v_bfe_u32 v157, v109, 16, 1
	v_add3_u32 v157, v109, v157, s76
	global_store_short_d16_hi v153, v157, s[16:17] offset:64
	v_bfe_u32 v158, v105, 16, 1
	v_add3_u32 v158, v105, v158, s76
	global_store_short_d16_hi v154, v158, s[16:17] offset:64
	v_bfe_u32 v155, v110, 16, 1
	v_add3_u32 v155, v110, v155, s76
	global_store_short_d16_hi v153, v155, s[16:17] offset:128
	v_bfe_u32 v156, v106, 16, 1
	v_add3_u32 v156, v106, v156, s76
	global_store_short_d16_hi v154, v156, s[16:17] offset:128
	v_bfe_u32 v157, v111, 16, 1
	v_add3_u32 v157, v111, v157, s76
	global_store_short_d16_hi v153, v157, s[16:17] offset:192
	v_bfe_u32 v158, v107, 16, 1
	v_add3_u32 v158, v107, v158, s76
	global_store_short_d16_hi v154, v158, s[16:17] offset:192
	v_add_u32_e32 v158, 0x80008, v152
	v_add_u32_e32 v159, 0x81008, v152
	v_bfe_u32 v160, v100, 16, 1
	v_add3_u32 v160, v100, v160, s76
	global_store_short_d16_hi v158, v160, s[16:17]
	v_bfe_u32 v161, v96, 16, 1
	v_add3_u32 v161, v96, v161, s76
	global_store_short_d16_hi v159, v161, s[16:17]
	v_bfe_u32 v162, v101, 16, 1
	v_add3_u32 v162, v101, v162, s76
	global_store_short_d16_hi v158, v162, s[16:17] offset:64
	v_bfe_u32 v163, v97, 16, 1
	v_add3_u32 v163, v97, v163, s76
	global_store_short_d16_hi v159, v163, s[16:17] offset:64
	v_bfe_u32 v160, v102, 16, 1
	v_add3_u32 v160, v102, v160, s76
	global_store_short_d16_hi v158, v160, s[16:17] offset:128
	v_bfe_u32 v161, v98, 16, 1
	v_add3_u32 v161, v98, v161, s76
	global_store_short_d16_hi v159, v161, s[16:17] offset:128
	v_bfe_u32 v162, v103, 16, 1
	v_add3_u32 v162, v103, v162, s76
	global_store_short_d16_hi v158, v162, s[16:17] offset:192
	v_bfe_u32 v163, v99, 16, 1
	v_add3_u32 v163, v99, v163, s76
	global_store_short_d16_hi v159, v163, s[16:17] offset:192
	v_add_u32_e32 v153, 0x2000, v152
	v_add_u32_e32 v154, 0x3000, v152
	v_bfe_u32 v155, v92, 16, 1
	v_add3_u32 v155, v92, v155, s76
	global_store_short_d16_hi v153, v155, s[16:17]
	v_bfe_u32 v156, v88, 16, 1
	v_add3_u32 v156, v88, v156, s76
	global_store_short_d16_hi v154, v156, s[16:17]
	v_bfe_u32 v157, v93, 16, 1
	v_add3_u32 v157, v93, v157, s76
	global_store_short_d16_hi v153, v157, s[16:17] offset:64
	v_bfe_u32 v158, v89, 16, 1
	v_add3_u32 v158, v89, v158, s76
	global_store_short_d16_hi v154, v158, s[16:17] offset:64
	v_bfe_u32 v155, v94, 16, 1
	v_add3_u32 v155, v94, v155, s76
	global_store_short_d16_hi v153, v155, s[16:17] offset:128
	v_bfe_u32 v156, v90, 16, 1
	v_add3_u32 v156, v90, v156, s76
	global_store_short_d16_hi v154, v156, s[16:17] offset:128
	v_bfe_u32 v157, v95, 16, 1
	v_add3_u32 v157, v95, v157, s76
	global_store_short_d16_hi v153, v157, s[16:17] offset:192
	v_bfe_u32 v158, v91, 16, 1
	v_add3_u32 v158, v91, v158, s76
	global_store_short_d16_hi v154, v158, s[16:17] offset:192
	v_add_u32_e32 v158, 0x82000, v152
	v_add_u32_e32 v159, 0x83000, v152
	v_bfe_u32 v160, v84, 16, 1
	v_add3_u32 v160, v84, v160, s76
	global_store_short_d16_hi v158, v160, s[16:17]
	v_bfe_u32 v161, v80, 16, 1
	v_add3_u32 v161, v80, v161, s76
	global_store_short_d16_hi v159, v161, s[16:17]
	v_bfe_u32 v162, v85, 16, 1
	v_add3_u32 v162, v85, v162, s76
	global_store_short_d16_hi v158, v162, s[16:17] offset:64
	v_bfe_u32 v163, v81, 16, 1
	v_add3_u32 v163, v81, v163, s76
	global_store_short_d16_hi v159, v163, s[16:17] offset:64
	v_bfe_u32 v160, v86, 16, 1
	v_add3_u32 v160, v86, v160, s76
	global_store_short_d16_hi v158, v160, s[16:17] offset:128
	v_bfe_u32 v161, v82, 16, 1
	v_add3_u32 v161, v82, v161, s76
	global_store_short_d16_hi v159, v161, s[16:17] offset:128
	v_bfe_u32 v162, v87, 16, 1
	v_add3_u32 v162, v87, v162, s76
	global_store_short_d16_hi v158, v162, s[16:17] offset:192
	v_bfe_u32 v163, v83, 16, 1
	v_add3_u32 v163, v83, v163, s76
	global_store_short_d16_hi v159, v163, s[16:17] offset:192
	v_add_u32_e32 v153, 0x2008, v152
	v_add_u32_e32 v154, 0x3008, v152
	v_bfe_u32 v155, v76, 16, 1
	v_add3_u32 v155, v76, v155, s76
	global_store_short_d16_hi v153, v155, s[16:17]
	v_bfe_u32 v156, v72, 16, 1
	v_add3_u32 v156, v72, v156, s76
	global_store_short_d16_hi v154, v156, s[16:17]
	v_bfe_u32 v157, v77, 16, 1
	v_add3_u32 v157, v77, v157, s76
	global_store_short_d16_hi v153, v157, s[16:17] offset:64
	v_bfe_u32 v158, v73, 16, 1
	v_add3_u32 v158, v73, v158, s76
	global_store_short_d16_hi v154, v158, s[16:17] offset:64
	v_bfe_u32 v155, v78, 16, 1
	v_add3_u32 v155, v78, v155, s76
	global_store_short_d16_hi v153, v155, s[16:17] offset:128
	v_bfe_u32 v156, v74, 16, 1
	v_add3_u32 v156, v74, v156, s76
	global_store_short_d16_hi v154, v156, s[16:17] offset:128
	v_bfe_u32 v157, v79, 16, 1
	v_add3_u32 v157, v79, v157, s76
	global_store_short_d16_hi v153, v157, s[16:17] offset:192
	v_bfe_u32 v158, v75, 16, 1
	v_add3_u32 v158, v75, v158, s76
	global_store_short_d16_hi v154, v158, s[16:17] offset:192
	v_add_u32_e32 v158, 0x82008, v152
	v_add_u32_e32 v159, 0x83008, v152
	v_bfe_u32 v160, v68, 16, 1
	v_add3_u32 v160, v68, v160, s76
	global_store_short_d16_hi v158, v160, s[16:17]
	v_bfe_u32 v161, v64, 16, 1
	v_add3_u32 v161, v64, v161, s76
	global_store_short_d16_hi v159, v161, s[16:17]
	v_bfe_u32 v162, v69, 16, 1
	v_add3_u32 v162, v69, v162, s76
	global_store_short_d16_hi v158, v162, s[16:17] offset:64
	v_bfe_u32 v163, v65, 16, 1
	v_add3_u32 v163, v65, v163, s76
	global_store_short_d16_hi v159, v163, s[16:17] offset:64
	v_bfe_u32 v160, v70, 16, 1
	v_add3_u32 v160, v70, v160, s76
	global_store_short_d16_hi v158, v160, s[16:17] offset:128
	v_bfe_u32 v161, v66, 16, 1
	v_add3_u32 v161, v66, v161, s76
	global_store_short_d16_hi v159, v161, s[16:17] offset:128
	v_bfe_u32 v162, v71, 16, 1
	v_add3_u32 v162, v71, v162, s76
	global_store_short_d16_hi v158, v162, s[16:17] offset:192
	v_bfe_u32 v163, v67, 16, 1
	v_add3_u32 v163, v67, v163, s76
	global_store_short_d16_hi v159, v163, s[16:17] offset:192
	v_add_u32_e32 v153, 0x8000, v152
	v_add_u32_e32 v154, 0x9000, v152
	v_bfe_u32 v155, v60, 16, 1
	v_add3_u32 v155, v60, v155, s76
	global_store_short_d16_hi v153, v155, s[16:17]
	v_bfe_u32 v156, v56, 16, 1
	v_add3_u32 v156, v56, v156, s76
	global_store_short_d16_hi v154, v156, s[16:17]
	v_bfe_u32 v157, v61, 16, 1
	v_add3_u32 v157, v61, v157, s76
	global_store_short_d16_hi v153, v157, s[16:17] offset:64
	v_bfe_u32 v158, v57, 16, 1
	v_add3_u32 v158, v57, v158, s76
	global_store_short_d16_hi v154, v158, s[16:17] offset:64
	v_bfe_u32 v155, v62, 16, 1
	v_add3_u32 v155, v62, v155, s76
	global_store_short_d16_hi v153, v155, s[16:17] offset:128
	v_bfe_u32 v156, v58, 16, 1
	v_add3_u32 v156, v58, v156, s76
	global_store_short_d16_hi v154, v156, s[16:17] offset:128
	v_bfe_u32 v157, v63, 16, 1
	v_add3_u32 v157, v63, v157, s76
	global_store_short_d16_hi v153, v157, s[16:17] offset:192
	v_bfe_u32 v158, v59, 16, 1
	v_add3_u32 v158, v59, v158, s76
	global_store_short_d16_hi v154, v158, s[16:17] offset:192
	v_add_u32_e32 v158, 0x88000, v152
	v_add_u32_e32 v159, 0x89000, v152
	v_bfe_u32 v160, v52, 16, 1
	v_add3_u32 v160, v52, v160, s76
	global_store_short_d16_hi v158, v160, s[16:17]
	v_bfe_u32 v161, v48, 16, 1
	v_add3_u32 v161, v48, v161, s76
	global_store_short_d16_hi v159, v161, s[16:17]
	v_bfe_u32 v162, v53, 16, 1
	v_add3_u32 v162, v53, v162, s76
	global_store_short_d16_hi v158, v162, s[16:17] offset:64
	v_bfe_u32 v163, v49, 16, 1
	v_add3_u32 v163, v49, v163, s76
	global_store_short_d16_hi v159, v163, s[16:17] offset:64
	v_bfe_u32 v160, v54, 16, 1
	v_add3_u32 v160, v54, v160, s76
	global_store_short_d16_hi v158, v160, s[16:17] offset:128
	v_bfe_u32 v161, v50, 16, 1
	v_add3_u32 v161, v50, v161, s76
	global_store_short_d16_hi v159, v161, s[16:17] offset:128
	v_bfe_u32 v162, v55, 16, 1
	v_add3_u32 v162, v55, v162, s76
	global_store_short_d16_hi v158, v162, s[16:17] offset:192
	v_bfe_u32 v163, v51, 16, 1
	v_add3_u32 v163, v51, v163, s76
	global_store_short_d16_hi v159, v163, s[16:17] offset:192
	v_add_u32_e32 v153, 0x8008, v152
	v_add_u32_e32 v154, 0x9008, v152
	v_bfe_u32 v155, v44, 16, 1
	v_add3_u32 v155, v44, v155, s76
	global_store_short_d16_hi v153, v155, s[16:17]
	v_bfe_u32 v156, v40, 16, 1
	v_add3_u32 v156, v40, v156, s76
	global_store_short_d16_hi v154, v156, s[16:17]
	v_bfe_u32 v157, v45, 16, 1
	v_add3_u32 v157, v45, v157, s76
	global_store_short_d16_hi v153, v157, s[16:17] offset:64
	v_bfe_u32 v158, v41, 16, 1
	v_add3_u32 v158, v41, v158, s76
	global_store_short_d16_hi v154, v158, s[16:17] offset:64
	v_bfe_u32 v155, v46, 16, 1
	v_add3_u32 v155, v46, v155, s76
	global_store_short_d16_hi v153, v155, s[16:17] offset:128
	v_bfe_u32 v156, v42, 16, 1
	v_add3_u32 v156, v42, v156, s76
	global_store_short_d16_hi v154, v156, s[16:17] offset:128
	v_bfe_u32 v157, v47, 16, 1
	v_add3_u32 v157, v47, v157, s76
	global_store_short_d16_hi v153, v157, s[16:17] offset:192
	v_bfe_u32 v158, v43, 16, 1
	v_add3_u32 v158, v43, v158, s76
	global_store_short_d16_hi v154, v158, s[16:17] offset:192
	v_add_u32_e32 v158, 0x88008, v152
	v_add_u32_e32 v159, 0x89008, v152
	v_bfe_u32 v160, v36, 16, 1
	v_add3_u32 v160, v36, v160, s76
	global_store_short_d16_hi v158, v160, s[16:17]
	v_bfe_u32 v161, v32, 16, 1
	v_add3_u32 v161, v32, v161, s76
	global_store_short_d16_hi v159, v161, s[16:17]
	v_bfe_u32 v162, v37, 16, 1
	v_add3_u32 v162, v37, v162, s76
	global_store_short_d16_hi v158, v162, s[16:17] offset:64
	v_bfe_u32 v163, v33, 16, 1
	v_add3_u32 v163, v33, v163, s76
	global_store_short_d16_hi v159, v163, s[16:17] offset:64
	v_bfe_u32 v160, v38, 16, 1
	v_add3_u32 v160, v38, v160, s76
	global_store_short_d16_hi v158, v160, s[16:17] offset:128
	v_bfe_u32 v161, v34, 16, 1
	v_add3_u32 v161, v34, v161, s76
	global_store_short_d16_hi v159, v161, s[16:17] offset:128
	v_bfe_u32 v162, v39, 16, 1
	v_add3_u32 v162, v39, v162, s76
	global_store_short_d16_hi v158, v162, s[16:17] offset:192
	v_bfe_u32 v163, v35, 16, 1
	v_add3_u32 v163, v35, v163, s76
	global_store_short_d16_hi v159, v163, s[16:17] offset:192
	v_add_u32_e32 v153, 0xa000, v152
	v_add_u32_e32 v154, 0xb000, v152
	v_bfe_u32 v155, v28, 16, 1
	v_add3_u32 v155, v28, v155, s76
	global_store_short_d16_hi v153, v155, s[16:17]
	v_bfe_u32 v156, v24, 16, 1
	v_add3_u32 v156, v24, v156, s76
	global_store_short_d16_hi v154, v156, s[16:17]
	v_bfe_u32 v157, v29, 16, 1
	v_add3_u32 v157, v29, v157, s76
	global_store_short_d16_hi v153, v157, s[16:17] offset:64
	v_bfe_u32 v158, v25, 16, 1
	v_add3_u32 v158, v25, v158, s76
	global_store_short_d16_hi v154, v158, s[16:17] offset:64
	v_bfe_u32 v155, v30, 16, 1
	v_add3_u32 v155, v30, v155, s76
	global_store_short_d16_hi v153, v155, s[16:17] offset:128
	v_bfe_u32 v156, v26, 16, 1
	v_add3_u32 v156, v26, v156, s76
	global_store_short_d16_hi v154, v156, s[16:17] offset:128
	v_bfe_u32 v157, v31, 16, 1
	v_add3_u32 v157, v31, v157, s76
	global_store_short_d16_hi v153, v157, s[16:17] offset:192
	v_bfe_u32 v158, v27, 16, 1
	v_add3_u32 v158, v27, v158, s76
	global_store_short_d16_hi v154, v158, s[16:17] offset:192
	v_add_u32_e32 v158, 0x8a000, v152
	v_add_u32_e32 v159, 0x8b000, v152
	v_bfe_u32 v160, v20, 16, 1
	v_add3_u32 v160, v20, v160, s76
	global_store_short_d16_hi v158, v160, s[16:17]
	v_bfe_u32 v161, v16, 16, 1
	v_add3_u32 v161, v16, v161, s76
	global_store_short_d16_hi v159, v161, s[16:17]
	v_bfe_u32 v162, v21, 16, 1
	v_add3_u32 v162, v21, v162, s76
	global_store_short_d16_hi v158, v162, s[16:17] offset:64
	v_bfe_u32 v163, v17, 16, 1
	v_add3_u32 v163, v17, v163, s76
	global_store_short_d16_hi v159, v163, s[16:17] offset:64
	v_bfe_u32 v160, v22, 16, 1
	v_add3_u32 v160, v22, v160, s76
	global_store_short_d16_hi v158, v160, s[16:17] offset:128
	v_bfe_u32 v161, v18, 16, 1
	v_add3_u32 v161, v18, v161, s76
	global_store_short_d16_hi v159, v161, s[16:17] offset:128
	v_bfe_u32 v162, v23, 16, 1
	v_add3_u32 v162, v23, v162, s76
	global_store_short_d16_hi v158, v162, s[16:17] offset:192
	v_bfe_u32 v163, v19, 16, 1
	v_add3_u32 v163, v19, v163, s76
	global_store_short_d16_hi v159, v163, s[16:17] offset:192
	v_add_u32_e32 v153, 0xa008, v152
	v_add_u32_e32 v154, 0xb008, v152
	v_bfe_u32 v155, v12, 16, 1
	v_add3_u32 v155, v12, v155, s76
	global_store_short_d16_hi v153, v155, s[16:17]
	v_bfe_u32 v156, v8, 16, 1
	v_add3_u32 v156, v8, v156, s76
	global_store_short_d16_hi v154, v156, s[16:17]
	v_bfe_u32 v157, v13, 16, 1
	v_add3_u32 v157, v13, v157, s76
	global_store_short_d16_hi v153, v157, s[16:17] offset:64
	v_bfe_u32 v158, v9, 16, 1
	v_add3_u32 v158, v9, v158, s76
	global_store_short_d16_hi v154, v158, s[16:17] offset:64
	v_bfe_u32 v155, v14, 16, 1
	v_add3_u32 v155, v14, v155, s76
	global_store_short_d16_hi v153, v155, s[16:17] offset:128
	v_bfe_u32 v156, v10, 16, 1
	v_add3_u32 v156, v10, v156, s76
	global_store_short_d16_hi v154, v156, s[16:17] offset:128
	v_bfe_u32 v157, v15, 16, 1
	v_add3_u32 v157, v15, v157, s76
	global_store_short_d16_hi v153, v157, s[16:17] offset:192
	v_bfe_u32 v158, v11, 16, 1
	v_add3_u32 v158, v11, v158, s76
	global_store_short_d16_hi v154, v158, s[16:17] offset:192
	v_add_u32_e32 v158, 0x8a008, v152
	v_add_u32_e32 v159, 0x8b008, v152
	v_bfe_u32 v160, v4, 16, 1
	v_add3_u32 v160, v4, v160, s76
	global_store_short_d16_hi v158, v160, s[16:17]
	v_bfe_u32 v161, v0, 16, 1
	v_add3_u32 v161, v0, v161, s76
	global_store_short_d16_hi v159, v161, s[16:17]
	v_bfe_u32 v162, v5, 16, 1
	v_add3_u32 v162, v5, v162, s76
	global_store_short_d16_hi v158, v162, s[16:17] offset:64
	v_bfe_u32 v163, v1, 16, 1
	v_add3_u32 v163, v1, v163, s76
	global_store_short_d16_hi v159, v163, s[16:17] offset:64
	v_bfe_u32 v160, v6, 16, 1
	v_add3_u32 v160, v6, v160, s76
	global_store_short_d16_hi v158, v160, s[16:17] offset:128
	v_bfe_u32 v161, v2, 16, 1
	v_add3_u32 v161, v2, v161, s76
	global_store_short_d16_hi v159, v161, s[16:17] offset:128
	v_bfe_u32 v162, v7, 16, 1
	v_add3_u32 v162, v7, v162, s76
	global_store_short_d16_hi v158, v162, s[16:17] offset:192
	v_bfe_u32 v163, v3, 16, 1
	v_add3_u32 v163, v3, v163, s76
	global_store_short_d16_hi v159, v163, s[16:17] offset:192
	s_mov_b64 s[2:3], exec
	s_branch .LBB0_306
